# combined: v42 + remaining W1 canonicalize folds + GEMM K-loop slot trimming + GEMM prologue second-batch hoist
# speedup vs baseline: 1.0093x; 1.0093x over previous
; #define PG8_STAGE(bufoff, gbase, voff) do { _Pragma("unroll") for (int _i = 0; _i < 2; ++_i) \
;         __builtin_amdgcn_global_load_lds((const unsigned*)((const char*)(gbase) + (voff)[_i]), (PG8_LAS unsigned*)(lds + (bufoff) + ldsw + _i * 8192), 16, 0, 0); } while (0)
; #define PG8_WAIT_V(n) asm volatile("s_waitcnt vmcnt(" #n ")" ::: "memory")
; #define PG8_BAR __builtin_amdgcn_s_barrier()
; template <class Epi, class Sched, bool ALIGN_EPI = false, bool SP2 = false>
; __device__ __forceinline__ void gemm_phase(PG8_LAS unsigned char* lds, const Gemm g, const Sched& S, const Epi& E) {
;     ...
;         PG8_STAGE(PG8_SB(0, 0), cB, voffB); PG8_STAGE(PG8_SB(0, 1), cB + hstepB, voffB); PG8_STAGE(PG8_SA(0, 0), cA, voffA); PG8_STAGE(PG8_SA(0, 1), cA + hstepA, voffA);
;         if (wr == 1) PG8_BAR;
;         PG8_WAIT_V(2); PG8_BAR;
;         PG8_STAGE(PG8_SB(1, 0), cB + kstep, voffB); PG8_STAGE(PG8_SA(1, 0), cA + kstep, voffA); PG8_STAGE(PG8_SB(1, 1), cB + hstepB + kstep, voffB);
;         PG8_WAIT_V(6); PG8_BAR;
.LBB0_154:
	s_ashr_i32 s11, s10, 31
	s_lshr_b32 s11, s11, 26
	s_add_i32 s11, s10, s11
	s_ashr_i32 s48, s11, 6
	s_lshl_b32 s49, s8, 6
	s_lshl_b32 s11, s8, 13
	s_lshl_b32 s8, s9, 5
	s_and_b32 s20, s8, 0x60
	s_mov_b64 s[8:9], 0x80
	s_add_i32 m0, s33, 0x18000
	v_lshl_add_u64 v[6:7], v[6:7], 0, s[8:9]
	s_lshl_b32 s13, s20, 7
	global_load_lds_dwordx4 v[6:7], off
	v_lshl_add_u64 v[4:5], v[4:5], 0, s[8:9]
	s_add_i32 m0, s33, 0x1a000
	s_add_i32 s50, s33, 0x8000
	s_add_i32 s51, s33, 0xa000
	global_load_lds_dwordx4 v[4:5], off
	v_lshl_add_u64 v[0:1], v[0:1], 0, s[8:9]
	s_mov_b32 m0, s50
	s_add_u32 s18, s40, 0x10080
	global_load_lds_dwordx4 v[0:1], off
	v_lshl_add_u64 v[0:1], v[2:3], 0, s[8:9]
	s_mov_b32 m0, s51
	s_addc_u32 s19, s41, 0
	global_load_lds_dwordx4 v[0:1], off
	s_add_i32 m0, s33, 0x1c000
	v_lshl_add_u64 v[0:1], s[18:19], 0, v[130:131]
	global_load_lds_dwordx4 v[0:1], off
	v_lshl_add_u64 v[0:1], s[18:19], 0, v[134:135]
	s_add_i32 m0, s33, 0x1e000
	v_bfe_u32 v144, v8, 4, 2
	global_load_lds_dwordx4 v[0:1], off
	v_and_b32_e32 v141, 15, v8
	v_lshlrev_b32_e32 v0, 4, v144
	v_lshlrev_b32_e32 v1, 2, v8
	v_lshl_or_b32 v0, v141, 6, v0
	v_and_b32_e32 v1, 32, v1
	v_bitop3_b32 v2, v0, s11, v1 bitop3:0xde
	v_bitop3_b32 v145, v0, s13, v1 bitop3:0xde
	v_lshlrev_b32_e32 v0, 12, v9
	v_and_b32_e32 v0, 0xffffe000, v0
	v_lshl_add_u32 v0, v10, 9, v0
	v_and_b32_e32 v1, 1, v9
	v_lshl_or_b32 v0, v1, 6, v0
	s_cmp_gt_i32 s10, 63
	v_lshl_add_u32 v136, v11, 1, v0
	v_lshlrev_b32_e32 v0, 12, v12
	s_cselect_b64 s[10:11], -1, 0
	s_add_i32 s52, s48, -2
	v_and_b32_e32 v0, 0xffffe000, v0
	s_waitcnt vmcnt(8)
	s_barrier
	s_waitcnt vmcnt(6)
	s_cmpk_lt_u32 s12, 0x100
	v_lshl_add_u32 v0, v13, 9, v0
	v_and_b32_e32 v1, 1, v12
	s_cselect_b64 s[12:13], -1, 0
	v_lshl_or_b32 v0, v1, 6, v0
	s_add_i32 s53, 0, 0x10000
	s_add_i32 s54, 0, 0x14000
	s_sext_i32_i8 s0, s0
	v_mov_b32_e32 v137, v131
	v_lshl_add_u32 v138, v14, 1, v0
	v_mov_b32_e32 v139, v131
	v_add_u32_e32 v146, s53, v145
	v_add_u32_e32 v147, s54, v145
	v_add_u32_e32 v148, 0, v2
	s_lshl_b32 s18, s20, 1
	v_mov_b32_e32 v149, 0xba800000
	v_mov_b32_e32 v150, 0x3a800000
	s_mov_b32 s55, 0
	s_barrier
	s_branch .LBB0_157

; #define PG8_STAGE(bufoff, gbase, voff) do { _Pragma("unroll") for (int _i = 0; _i < 2; ++_i) \
;         __builtin_amdgcn_global_load_lds((const unsigned*)((const char*)(gbase) + (voff)[_i]), (PG8_LAS unsigned*)(lds + (bufoff) + ldsw + _i * 8192), 16, 0, 0); } while (0)
; #define PG8_WAIT_V(n) asm volatile("s_waitcnt vmcnt(" #n ")" ::: "memory")
; #define PG8_BAR __builtin_amdgcn_s_barrier()
; template <class Epi, class Sched, bool ALIGN_EPI = false, bool SP2 = false>
; __device__ __forceinline__ void gemm_phase(PG8_LAS unsigned char* lds, const Gemm g, const Sched& S, const Epi& E) {
;     ...
;         PG8_STAGE(PG8_SB(0, 0), cB, voffB); PG8_STAGE(PG8_SB(0, 1), cB + hstepB, voffB); PG8_STAGE(PG8_SA(0, 0), cA, voffA); PG8_STAGE(PG8_SA(0, 1), cA + hstepA, voffA);
;         if (wr == 1) PG8_BAR;
;         PG8_WAIT_V(2); PG8_BAR;
;         PG8_STAGE(PG8_SB(1, 0), cB + kstep, voffB); PG8_STAGE(PG8_SA(1, 0), cA + kstep, voffA); PG8_STAGE(PG8_SB(1, 1), cB + hstepB + kstep, voffB);
;         PG8_WAIT_V(6); PG8_BAR;
.LBB0_294:
	s_and_b32 s33, s11, 3
	v_bfe_u32 v157, v11, 4, 2
	s_ashr_i32 s11, s16, 31
	v_and_b32_e32 v156, 15, v11
	s_lshr_b32 s11, s11, 26
	v_lshlrev_b32_e32 v15, 4, v157
	v_lshlrev_b32_e32 v11, 2, v11
	s_add_i32 s11, s16, s11
	s_lshl_b32 s12, s13, 6
	v_lshl_or_b32 v15, v156, 6, v15
	s_lshl_b32 s13, s13, 13
	v_and_b32_e32 v11, 32, v11
	s_lshl_b32 s14, s33, 12
	s_add_i32 m0, s3, 0x18000
	v_lshl_add_u64 v[6:7], v[6:7], 0, s[26:27]
	s_ashr_i32 s11, s11, 6
	v_bitop3_b32 v16, v15, s13, v11 bitop3:0xde
	s_lshl_b32 s13, s33, 5
	v_bitop3_b32 v158, v15, s14, v11 bitop3:0xde
	global_load_lds_dwordx4 v[6:7], off
	v_lshl_add_u64 v[4:5], v[4:5], 0, s[26:27]
	s_add_i32 m0, s3, 0x1a000
	s_add_i32 s14, s3, 0x8000
	s_add_i32 s15, s3, 0xa000
	global_load_lds_dwordx4 v[4:5], off
	v_lshl_add_u64 v[0:1], v[0:1], 0, s[26:27]
	s_mov_b32 m0, s14
	s_add_u32 s28, s46, 0x40080
	global_load_lds_dwordx4 v[0:1], off
	v_lshl_add_u64 v[0:1], v[2:3], 0, s[26:27]
	s_mov_b32 m0, s15
	s_addc_u32 s29, s47, 0
	global_load_lds_dwordx4 v[0:1], off
	s_add_i32 m0, s3, 0x1c000
	v_lshl_add_u64 v[0:1], s[28:29], 0, v[194:195]
	global_load_lds_dwordx4 v[0:1], off
	v_lshl_add_u64 v[0:1], s[28:29], 0, v[132:133]
	s_add_i32 m0, s3, 0x1e000
	s_cmp_gt_i32 s16, 63
	global_load_lds_dwordx4 v[0:1], off
	v_lshlrev_b32_e32 v0, 14, v8
	v_and_b32_e32 v0, 0xffff8000, v0
	v_lshl_add_u32 v0, v9, 11, v0
	v_and_b32_e32 v1, 1, v8
	v_lshl_or_b32 v0, v1, 6, v0
	v_lshl_add_u32 v134, v10, 1, v0
	v_lshlrev_b32_e32 v0, 14, v12
	s_cselect_b64 s[68:69], -1, 0
	s_add_i32 s16, s11, -2
	v_and_b32_e32 v0, 0xffff8000, v0
	s_waitcnt vmcnt(8)
	s_barrier
	s_waitcnt vmcnt(6)
	s_cmpk_lt_u32 s17, 0x100
	v_lshl_add_u32 v0, v13, 11, v0
	v_and_b32_e32 v1, 1, v12
	s_cselect_b64 s[76:77], -1, 0
	s_cmp_eq_u32 s33, 0
	v_readlane_b32 s4, v255, 17
	v_lshl_or_b32 v0, v1, 6, v0
	s_mov_b32 s17, 0
	s_cselect_b64 s[80:81], -1, 0
	s_mov_b32 s35, s60
	s_lshr_b32 s28, s4, 10
	v_mov_b32_e32 v135, v195
	v_lshl_add_u32 v136, v14, 1, v0
	v_mov_b32_e32 v137, v195
	v_add_u32_e32 v159, 0, v16
	s_barrier
	s_branch .LBB0_297

; #define PG8_STAGE(bufoff, gbase, voff) do { _Pragma("unroll") for (int _i = 0; _i < 2; ++_i) \
;         __builtin_amdgcn_global_load_lds((const unsigned*)((const char*)(gbase) + (voff)[_i]), (PG8_LAS unsigned*)(lds + (bufoff) + ldsw + _i * 8192), 16, 0, 0); } while (0)
; #define PG8_WAIT_V(n) asm volatile("s_waitcnt vmcnt(" #n ")" ::: "memory")
; #define PG8_BAR __builtin_amdgcn_s_barrier()
; template <class Epi, class Sched, bool ALIGN_EPI = false, bool SP2 = false>
; __device__ __forceinline__ void gemm_phase(PG8_LAS unsigned char* lds, const Gemm g, const Sched& S, const Epi& E) {
;     ...
;         PG8_STAGE(PG8_SB(0, 0), cB, voffB); PG8_STAGE(PG8_SB(0, 1), cB + hstepB, voffB); PG8_STAGE(PG8_SA(0, 0), cA, voffA); PG8_STAGE(PG8_SA(0, 1), cA + hstepA, voffA);
;         if (wr == 1) PG8_BAR;
;         PG8_WAIT_V(2); PG8_BAR;
;         PG8_STAGE(PG8_SB(1, 0), cB + kstep, voffB); PG8_STAGE(PG8_SA(1, 0), cA + kstep, voffA); PG8_STAGE(PG8_SB(1, 1), cB + hstepB + kstep, voffB);
;         PG8_WAIT_V(6); PG8_BAR;
.LBB0_495:
	s_and_b32 s12, s2, 3
	s_ashr_i32 s2, s15, 31
	v_bfe_u32 v153, v11, 4, 2
	s_lshr_b32 s2, s2, 26
	v_and_b32_e32 v152, 15, v11
	s_add_i32 s2, s15, s2
	v_lshlrev_b32_e32 v15, 4, v153
	v_lshlrev_b32_e32 v11, 2, v11
	s_ashr_i32 s13, s2, 6
	s_lshl_b32 s29, s3, 6
	v_lshl_or_b32 v15, v152, 6, v15
	s_lshl_b32 s2, s3, 13
	v_and_b32_e32 v11, 32, v11
	s_lshl_b32 s3, s12, 12
	s_add_i32 m0, s9, 0x18000
	v_lshl_add_u64 v[6:7], v[6:7], 0, s[26:27]
	v_bitop3_b32 v16, v15, s2, v11 bitop3:0xde
	s_lshl_b32 s2, s12, 5
	v_bitop3_b32 v154, v15, s3, v11 bitop3:0xde
	global_load_lds_dwordx4 v[6:7], off
	v_lshl_add_u64 v[4:5], v[4:5], 0, s[26:27]
	s_add_i32 m0, s9, 0x1a000
	s_add_i32 s3, s9, 0x8000
	s_add_i32 s55, s9, 0xa000
	global_load_lds_dwordx4 v[4:5], off
	v_lshl_add_u64 v[0:1], v[0:1], 0, s[26:27]
	s_mov_b32 m0, s3
	s_add_u32 s16, s44, 0x10080
	global_load_lds_dwordx4 v[0:1], off
	v_lshl_add_u64 v[0:1], v[2:3], 0, s[26:27]
	s_mov_b32 m0, s55
	s_addc_u32 s17, s45, 0
	global_load_lds_dwordx4 v[0:1], off
	s_add_i32 m0, s9, 0x1c000
	v_lshl_add_u64 v[0:1], s[16:17], 0, v[194:195]
	global_load_lds_dwordx4 v[0:1], off
	v_lshl_add_u64 v[0:1], s[16:17], 0, v[132:133]
	s_add_i32 m0, s9, 0x1e000
	s_cmp_gt_i32 s15, 63
	global_load_lds_dwordx4 v[0:1], off
	v_lshlrev_b32_e32 v0, 13, v8
	v_and_b32_e32 v0, 0xffffc000, v0
	v_lshl_add_u32 v0, v9, 10, v0
	v_and_b32_e32 v1, 1, v8
	v_lshl_or_b32 v0, v1, 6, v0
	v_lshl_add_u32 v134, v10, 1, v0
	v_lshlrev_b32_e32 v0, 13, v12
	v_and_b32_e32 v0, 0xffffc000, v0
	s_waitcnt vmcnt(8)
	s_barrier
	s_waitcnt vmcnt(6)
	s_cselect_b64 s[84:85], -1, 0
	s_add_i32 s58, s13, -2
	v_lshl_add_u32 v0, v13, 10, v0
	v_and_b32_e32 v1, 1, v12
	s_cmpk_lt_u32 s14, 0x100
	v_lshl_or_b32 v0, v1, 6, v0
	s_cselect_b64 s[86:87], -1, 0
	s_mov_b32 s81, s60
	s_lshr_b32 s59, s80, 3
	v_mov_b32_e32 v135, v195
	v_lshl_add_u32 v136, v14, 1, v0
	v_mov_b32_e32 v137, v195
	s_mov_b32 s14, 0
	v_add_u32_e32 v155, 0, v16
	s_barrier
	s_branch .LBB0_498

; #define PG8_STAGE(bufoff, gbase, voff) do { _Pragma("unroll") for (int _i = 0; _i < 2; ++_i) \
;         __builtin_amdgcn_global_load_lds((const unsigned*)((const char*)(gbase) + (voff)[_i]), (PG8_LAS unsigned*)(lds + (bufoff) + ldsw + _i * 8192), 16, 0, 0); } while (0)
; #define PG8_WAIT_V(n) asm volatile("s_waitcnt vmcnt(" #n ")" ::: "memory")
; #define PG8_BAR __builtin_amdgcn_s_barrier()
; template <class Epi, class Sched, bool ALIGN_EPI = false, bool SP2 = false>
; __device__ __forceinline__ void gemm_phase(PG8_LAS unsigned char* lds, const Gemm g, const Sched& S, const Epi& E) {
;     ...
;         PG8_STAGE(PG8_SB(0, 0), cB, voffB); PG8_STAGE(PG8_SB(0, 1), cB + hstepB, voffB); PG8_STAGE(PG8_SA(0, 0), cA, voffA); PG8_STAGE(PG8_SA(0, 1), cA + hstepA, voffA);
;         if (wr == 1) PG8_BAR;
;         PG8_WAIT_V(2); PG8_BAR;
;         PG8_STAGE(PG8_SB(1, 0), cB + kstep, voffB); PG8_STAGE(PG8_SA(1, 0), cA + kstep, voffA); PG8_STAGE(PG8_SB(1, 1), cB + hstepB + kstep, voffB);
;         PG8_WAIT_V(6); PG8_BAR;
.LBB0_562:
	v_bfe_u32 v147, v10, 4, 2
	v_and_b32_e32 v146, 15, v10
	v_lshlrev_b32_e32 v15, 4, v147
	v_lshlrev_b32_e32 v10, 2, v10
	s_lshl_b32 s12, s13, 6
	v_lshl_or_b32 v15, v146, 6, v15
	s_lshl_b32 s13, s13, 13
	v_and_b32_e32 v10, 32, v10
	s_ashr_i32 s11, s15, 31
	v_bitop3_b32 v16, v15, s13, v10 bitop3:0xde
	s_lshl_b32 s13, s14, 5
	s_lshr_b32 s11, s11, 26
	s_and_b32 s33, s13, 0x60
	s_add_i32 s11, s15, s11
	s_lshl_b32 s13, s33, 7
	s_add_i32 m0, s3, 0x18000
	v_lshl_add_u64 v[6:7], v[6:7], 0, s[26:27]
	s_ashr_i32 s11, s11, 6
	v_bitop3_b32 v148, v15, s13, v10 bitop3:0xde
	global_load_lds_dwordx4 v[6:7], off
	v_lshl_add_u64 v[4:5], v[4:5], 0, s[26:27]
	s_add_i32 m0, s3, 0x1a000
	s_add_i32 s13, s3, 0x8000
	s_add_i32 s14, s3, 0xa000
	global_load_lds_dwordx4 v[4:5], off
	v_lshl_add_u64 v[0:1], v[0:1], 0, s[26:27]
	s_mov_b32 m0, s13
	s_add_u32 s28, s86, 0x8080
	global_load_lds_dwordx4 v[0:1], off
	v_lshl_add_u64 v[0:1], v[2:3], 0, s[26:27]
	s_mov_b32 m0, s14
	s_addc_u32 s29, s87, 0
	global_load_lds_dwordx4 v[0:1], off
	s_add_i32 m0, s3, 0x1c000
	v_lshl_add_u64 v[0:1], s[28:29], 0, v[194:195]
	global_load_lds_dwordx4 v[0:1], off
	v_lshl_add_u64 v[0:1], s[28:29], 0, v[132:133]
	s_add_i32 m0, s3, 0x1e000
	s_cmp_gt_i32 s15, 63
	global_load_lds_dwordx4 v[0:1], off
	v_lshlrev_b32_e32 v0, 13, v8
	v_and_b32_e32 v0, 0xffffc000, v0
	v_lshl_add_u32 v0, v9, 10, v0
	v_and_b32_e32 v1, 1, v8
	v_lshl_or_b32 v0, v1, 6, v0
	v_lshl_add_u32 v134, v11, 1, v0
	v_lshlrev_b32_e32 v0, 13, v12
	v_and_b32_e32 v0, 0xffffc000, v0
	s_waitcnt vmcnt(8)
	s_barrier
	s_waitcnt vmcnt(6)
	s_cselect_b64 s[40:41], -1, 0
	s_add_i32 s15, s11, -2
	v_lshl_add_u32 v0, v13, 10, v0
	v_and_b32_e32 v1, 1, v12
	s_cmpk_lt_u32 s16, 0x100
	v_readlane_b32 s4, v255, 17
	v_lshl_or_b32 v0, v1, 6, v0
	s_cselect_b64 s[42:43], -1, 0
	s_mov_b32 s45, s60
	s_lshr_b32 s16, s4, 9
	v_mov_b32_e32 v135, v195
	v_lshl_add_u32 v136, v14, 1, v0
	v_mov_b32_e32 v137, v195
	s_mov_b32 s17, 0
	v_add_u32_e32 v149, 0, v16
	s_lshl_b32 s46, s33, 1
	s_barrier
	s_branch .LBB0_565

; #define PG8_STAGE(bufoff, gbase, voff) do { _Pragma("unroll") for (int _i = 0; _i < 2; ++_i) \
;         __builtin_amdgcn_global_load_lds((const unsigned*)((const char*)(gbase) + (voff)[_i]), (PG8_LAS unsigned*)(lds + (bufoff) + ldsw + _i * 8192), 16, 0, 0); } while (0)
; #define PG8_WAIT_V(n) asm volatile("s_waitcnt vmcnt(" #n ")" ::: "memory")
; #define PG8_BAR __builtin_amdgcn_s_barrier()
; template <class Epi, class Sched, bool ALIGN_EPI = false, bool SP2 = false>
; __device__ __forceinline__ void gemm_phase(PG8_LAS unsigned char* lds, const Gemm g, const Sched& S, const Epi& E) {
;     ...
;         PG8_STAGE(PG8_SB(0, 0), cB, voffB); PG8_STAGE(PG8_SB(0, 1), cB + hstepB, voffB); PG8_STAGE(PG8_SA(0, 0), cA, voffA); PG8_STAGE(PG8_SA(0, 1), cA + hstepA, voffA);
;         if (wr == 1) PG8_BAR;
;         PG8_WAIT_V(2); PG8_BAR;
;         PG8_STAGE(PG8_SB(1, 0), cB + kstep, voffB); PG8_STAGE(PG8_SA(1, 0), cA + kstep, voffA); PG8_STAGE(PG8_SB(1, 1), cB + hstepB + kstep, voffB);
;         PG8_WAIT_V(6); PG8_BAR;
.LBB0_611:
	v_bfe_u32 v153, v14, 4, 2
	v_and_b32_e32 v152, 15, v14
	s_ashr_i32 s16, s39, 31
	v_lshlrev_b32_e32 v15, 4, v153
	v_lshlrev_b32_e32 v14, 2, v14
	s_lshl_b32 s28, s28, 5
	s_lshr_b32 s16, s16, 26
	s_lshl_b32 s17, s29, 6
	v_lshl_or_b32 v15, v152, 6, v15
	s_lshl_b32 s29, s29, 13
	v_and_b32_e32 v14, 32, v14
	s_and_b32 s28, s28, 0x60
	s_add_i32 s16, s39, s16
	v_bitop3_b32 v16, v15, s29, v14 bitop3:0xde
	s_lshl_b32 s29, s28, 7
	s_add_i32 m0, s12, 0x18000
	v_lshl_add_u64 v[6:7], v[6:7], 0, s[26:27]
	s_ashr_i32 s16, s16, 6
	v_bitop3_b32 v154, v15, s29, v14 bitop3:0xde
	global_load_lds_dwordx4 v[6:7], off
	v_lshl_add_u64 v[4:5], v[4:5], 0, s[26:27]
	s_add_i32 m0, s12, 0x1a000
	s_add_i32 s29, s12, 0x8000
	s_add_i32 s33, s12, 0xa000
	global_load_lds_dwordx4 v[4:5], off
	v_lshl_add_u64 v[0:1], v[0:1], 0, s[26:27]
	s_mov_b32 m0, s29
	s_add_u32 s46, s84, 0x20080
	global_load_lds_dwordx4 v[0:1], off
	v_lshl_add_u64 v[0:1], v[2:3], 0, s[26:27]
	s_mov_b32 m0, s33
	s_addc_u32 s47, s85, 0
	global_load_lds_dwordx4 v[0:1], off
	s_add_i32 m0, s12, 0x1c000
	v_lshl_add_u64 v[0:1], s[46:47], 0, v[136:137]
	global_load_lds_dwordx4 v[0:1], off
	v_lshl_add_u64 v[0:1], s[46:47], 0, v[132:133]
	s_add_i32 m0, s12, 0x1e000
	s_cmp_gt_i32 s39, 63
	global_load_lds_dwordx4 v[0:1], off
	v_lshlrev_b32_e32 v0, 11, v12
	v_and_b32_e32 v0, 0xfffff000, v0
	v_lshl_add_u32 v0, v11, 8, v0
	v_and_b32_e32 v1, 1, v12
	v_lshl_or_b32 v0, v1, 6, v0
	v_lshl_add_u32 v140, v13, 1, v0
	v_lshlrev_b32_e32 v0, 11, v8
	v_and_b32_e32 v0, 0xfffff000, v0
	s_waitcnt vmcnt(8)
	s_barrier
	s_waitcnt vmcnt(6)
	s_cselect_b64 s[46:47], -1, 0
	s_add_i32 s55, s16, -2
	v_lshl_add_u32 v0, v9, 8, v0
	v_and_b32_e32 v1, 1, v8
	s_cmpk_lt_u32 s38, 0x100
	v_lshl_or_b32 v0, v1, 6, v0
	s_cselect_b64 s[48:49], -1, 0
	s_mov_b32 s45, s60
	v_mov_b32_e32 v141, v195
	v_lshl_add_u32 v142, v10, 1, v0
	v_mov_b32_e32 v143, v195
	s_mov_b32 s58, 0
	v_add_u32_e32 v155, 0, v16
	s_barrier
	s_branch .LBB0_614

; #define PG8_STAGE(bufoff, gbase, voff) do { _Pragma("unroll") for (int _i = 0; _i < 2; ++_i) \
;         __builtin_amdgcn_global_load_lds((const unsigned*)((const char*)(gbase) + (voff)[_i]), (PG8_LAS unsigned*)(lds + (bufoff) + ldsw + _i * 8192), 16, 0, 0); } while (0)
; #define PG8_WAIT_V(n) asm volatile("s_waitcnt vmcnt(" #n ")" ::: "memory")
; #define PG8_BAR __builtin_amdgcn_s_barrier()
; template <class Epi, class Sched, bool ALIGN_EPI = false, bool SP2 = false>
; __device__ __forceinline__ void gemm_phase(PG8_LAS unsigned char* lds, const Gemm g, const Sched& S, const Epi& E) {
;     ...
;         PG8_STAGE(PG8_SB(0, 0), cB, voffB); PG8_STAGE(PG8_SB(0, 1), cB + hstepB, voffB); PG8_STAGE(PG8_SA(0, 0), cA, voffA); PG8_STAGE(PG8_SA(0, 1), cA + hstepA, voffA);
;         if (wr == 1) PG8_BAR;
;         PG8_WAIT_V(2); PG8_BAR;
;         PG8_STAGE(PG8_SB(1, 0), cB + kstep, voffB); PG8_STAGE(PG8_SA(1, 0), cA + kstep, voffA); PG8_STAGE(PG8_SB(1, 1), cB + hstepB + kstep, voffB);
;         PG8_WAIT_V(6); PG8_BAR;
.LBB0_922:
	v_bfe_u32 v169, v11, 4, 2
	s_and_b32 s14, s11, 3
	v_and_b32_e32 v168, 15, v11
	s_ashr_i32 s11, s16, 31
	v_lshlrev_b32_e32 v15, 4, v169
	v_lshlrev_b32_e32 v11, 2, v11
	s_lshr_b32 s11, s11, 26
	s_lshl_b32 s12, s13, 6
	v_lshl_or_b32 v15, v168, 6, v15
	s_lshl_b32 s13, s13, 13
	v_and_b32_e32 v11, 32, v11
	s_add_i32 s11, s16, s11
	v_bitop3_b32 v16, v15, s13, v11 bitop3:0xde
	s_lshl_b32 s13, s14, 5
	s_lshl_b32 s14, s14, 12
	s_add_i32 m0, s3, 0x18000
	v_lshl_add_u64 v[6:7], v[6:7], 0, s[26:27]
	s_ashr_i32 s11, s11, 6
	v_bitop3_b32 v170, v15, s14, v11 bitop3:0xde
	global_load_lds_dwordx4 v[6:7], off
	v_lshl_add_u64 v[4:5], v[4:5], 0, s[26:27]
	s_add_i32 m0, s3, 0x1a000
	s_add_i32 s14, s3, 0x8000
	s_add_i32 s15, s3, 0xa000
	global_load_lds_dwordx4 v[4:5], off
	v_lshl_add_u64 v[0:1], v[0:1], 0, s[26:27]
	s_mov_b32 m0, s14
	s_add_u32 s28, s86, 0x40080
	global_load_lds_dwordx4 v[0:1], off
	v_lshl_add_u64 v[0:1], v[2:3], 0, s[26:27]
	s_mov_b32 m0, s15
	s_addc_u32 s29, s87, 0
	global_load_lds_dwordx4 v[0:1], off
	s_add_i32 m0, s3, 0x1c000
	v_lshl_add_u64 v[0:1], s[28:29], 0, v[140:141]
	global_load_lds_dwordx4 v[0:1], off
	v_lshl_add_u64 v[0:1], s[28:29], 0, v[144:145]
	s_add_i32 m0, s3, 0x1e000
	s_cmp_gt_i32 s16, 63
	global_load_lds_dwordx4 v[0:1], off
	v_lshlrev_b32_e32 v0, 14, v8
	v_and_b32_e32 v0, 0xffff8000, v0
	v_lshl_add_u32 v0, v9, 11, v0
	v_and_b32_e32 v1, 1, v8
	v_lshl_or_b32 v0, v1, 6, v0
	v_lshl_add_u32 v146, v10, 1, v0
	v_lshlrev_b32_e32 v0, 14, v12
	s_cselect_b64 s[48:49], -1, 0
	s_add_i32 s16, s11, -2
	v_and_b32_e32 v0, 0xffff8000, v0
	s_waitcnt vmcnt(8)
	s_barrier
	s_waitcnt vmcnt(6)
	s_cmpk_lt_u32 s17, 0x100
	v_lshl_add_u32 v0, v13, 11, v0
	v_and_b32_e32 v1, 1, v12
	s_cselect_b64 s[52:53], -1, 0
	s_bitcmp0_b32 s17, 6
	v_lshl_or_b32 v0, v1, 6, v0
	s_mov_b32 s17, 0
	s_cselect_b64 s[38:39], -1, 0
	s_mov_b32 s47, s60
	v_mov_b32_e32 v147, v195
	v_lshl_add_u32 v148, v14, 1, v0
	v_mov_b32_e32 v149, v195
	v_add_u32_e32 v171, 0, v16
	s_barrier
	s_branch .LBB0_925

; #define PG8_STAGE(bufoff, gbase, voff) do { _Pragma("unroll") for (int _i = 0; _i < 2; ++_i) \
;         __builtin_amdgcn_global_load_lds((const unsigned*)((const char*)(gbase) + (voff)[_i]), (PG8_LAS unsigned*)(lds + (bufoff) + ldsw + _i * 8192), 16, 0, 0); } while (0)
; #define PG8_WAIT_V(n) asm volatile("s_waitcnt vmcnt(" #n ")" ::: "memory")
; #define PG8_BAR __builtin_amdgcn_s_barrier()
; template <class Epi, class Sched, bool ALIGN_EPI = false, bool SP2 = false>
; __device__ __forceinline__ void gemm_phase(PG8_LAS unsigned char* lds, const Gemm g, const Sched& S, const Epi& E) {
;     ...
;         PG8_STAGE(PG8_SB(0, 0), cB, voffB); PG8_STAGE(PG8_SB(0, 1), cB + hstepB, voffB); PG8_STAGE(PG8_SA(0, 0), cA, voffA); PG8_STAGE(PG8_SA(0, 1), cA + hstepA, voffA);
;         if (wr == 1) PG8_BAR;
;         PG8_WAIT_V(2); PG8_BAR;
;         PG8_STAGE(PG8_SB(1, 0), cB + kstep, voffB); PG8_STAGE(PG8_SA(1, 0), cA + kstep, voffA); PG8_STAGE(PG8_SB(1, 1), cB + hstepB + kstep, voffB);
;         PG8_WAIT_V(6); PG8_BAR;
.LBB0_1012:
	v_bfe_u32 v141, v14, 4, 2
	v_and_b32_e32 v140, 15, v14
	s_ashr_i32 s15, s33, 31
	v_lshlrev_b32_e32 v15, 4, v141
	v_lshlrev_b32_e32 v14, 2, v14
	s_lshl_b32 s17, s17, 5
	s_lshr_b32 s15, s15, 26
	s_lshl_b32 s16, s28, 6
	v_lshl_or_b32 v15, v140, 6, v15
	s_lshl_b32 s28, s28, 13
	v_and_b32_e32 v14, 32, v14
	s_and_b32 s17, s17, 0x60
	s_add_i32 s15, s33, s15
	v_bitop3_b32 v16, v15, s28, v14 bitop3:0xde
	s_lshl_b32 s28, s17, 7
	s_add_i32 m0, s11, 0x18000
	v_lshl_add_u64 v[6:7], v[6:7], 0, s[26:27]
	s_ashr_i32 s15, s15, 6
	v_bitop3_b32 v142, v15, s28, v14 bitop3:0xde
	global_load_lds_dwordx4 v[6:7], off
	v_lshl_add_u64 v[4:5], v[4:5], 0, s[26:27]
	s_add_i32 m0, s11, 0x1a000
	s_add_i32 s28, s11, 0x8000
	s_add_i32 s29, s11, 0xa000
	global_load_lds_dwordx4 v[4:5], off
	v_lshl_add_u64 v[0:1], v[0:1], 0, s[26:27]
	s_mov_b32 m0, s28
	s_add_u32 s38, s86, 0x40080
	global_load_lds_dwordx4 v[0:1], off
	v_lshl_add_u64 v[0:1], v[2:3], 0, s[26:27]
	s_mov_b32 m0, s29
	s_addc_u32 s39, s87, 0
	global_load_lds_dwordx4 v[0:1], off
	s_add_i32 m0, s11, 0x1c000
	v_lshl_add_u64 v[0:1], s[38:39], 0, v[132:133]
	global_load_lds_dwordx4 v[0:1], off
	v_lshl_add_u64 v[0:1], s[38:39], 0, v[128:129]
	s_add_i32 m0, s11, 0x1e000
	s_cmp_gt_i32 s33, 63
	global_load_lds_dwordx4 v[0:1], off
	v_lshlrev_b32_e32 v0, 14, v12
	v_and_b32_e32 v0, 0xffff8000, v0
	v_lshl_add_u32 v0, v11, 11, v0
	v_and_b32_e32 v1, 1, v12
	v_lshl_or_b32 v0, v1, 6, v0
	v_lshl_add_u32 v136, v13, 1, v0
	v_lshlrev_b32_e32 v0, 14, v8
	v_and_b32_e32 v0, 0xffff8000, v0
	s_waitcnt vmcnt(8)
	s_barrier
	s_waitcnt vmcnt(6)
	s_cselect_b64 s[42:43], -1, 0
	s_add_i32 s33, s15, -2
	v_lshl_add_u32 v0, v9, 11, v0
	v_and_b32_e32 v1, 1, v8
	s_cmpk_lt_u32 s35, 0x100
	v_lshl_or_b32 v0, v1, 6, v0
	s_cselect_b64 s[44:45], -1, 0
	s_mov_b32 s35, s60
	v_mov_b32_e32 v137, v195
	v_lshl_add_u32 v138, v10, 1, v0
	v_mov_b32_e32 v139, v195
	s_mov_b32 s47, 0
	v_add_u32_e32 v143, 0, v16
	s_barrier
	s_branch .LBB0_1015

; #define PG8_STAGE(bufoff, gbase, voff) do { _Pragma("unroll") for (int _i = 0; _i < 2; ++_i) \
;         __builtin_amdgcn_global_load_lds((const unsigned*)((const char*)(gbase) + (voff)[_i]), (PG8_LAS unsigned*)(lds + (bufoff) + ldsw + _i * 8192), 16, 0, 0); } while (0)
; #define PG8_WAIT_V(n) asm volatile("s_waitcnt vmcnt(" #n ")" ::: "memory")
; #define PG8_BAR __builtin_amdgcn_s_barrier()
; template <class Epi, class Sched, bool ALIGN_EPI = false, bool SP2 = false>
; __device__ __forceinline__ void gemm_phase(PG8_LAS unsigned char* lds, const Gemm g, const Sched& S, const Epi& E) {
;     ...
;         PG8_STAGE(PG8_SB(0, 0), cB, voffB); PG8_STAGE(PG8_SB(0, 1), cB + hstepB, voffB); PG8_STAGE(PG8_SA(0, 0), cA, voffA); PG8_STAGE(PG8_SA(0, 1), cA + hstepA, voffA);
;         if (wr == 1) PG8_BAR;
;         PG8_WAIT_V(2); PG8_BAR;
;         PG8_STAGE(PG8_SB(1, 0), cB + kstep, voffB); PG8_STAGE(PG8_SA(1, 0), cA + kstep, voffA); PG8_STAGE(PG8_SB(1, 1), cB + hstepB + kstep, voffB);
;         PG8_WAIT_V(6); PG8_BAR;
.LBB0_1207:
	s_ashr_i32 s2, s15, 31
	v_bfe_u32 v177, v12, 4, 2
	s_lshr_b32 s2, s2, 26
	v_and_b32_e32 v176, 15, v12
	s_add_i32 s2, s15, s2
	v_lshlrev_b32_e32 v13, 4, v177
	v_lshlrev_b32_e32 v12, 2, v12
	s_ashr_i32 s13, s2, 6
	s_lshl_b32 s2, s3, 6
	v_lshl_or_b32 v13, v176, 6, v13
	s_lshl_b32 s3, s3, 13
	v_and_b32_e32 v12, 32, v12
	v_bitop3_b32 v14, v13, s3, v12 bitop3:0xde
	s_lshl_b32 s3, s14, 5
	s_and_b32 s3, s3, 0x60
	s_add_i32 m0, s85, 0x18000
	v_lshl_add_u64 v[0:1], v[0:1], 0, s[26:27]
	s_lshl_b32 s14, s3, 7
	global_load_lds_dwordx4 v[0:1], off
	v_lshl_add_u64 v[0:1], v[2:3], 0, s[26:27]
	s_add_i32 m0, s85, 0x1a000
	s_add_i32 s64, s85, 0x8000
	v_bitop3_b32 v178, v13, s14, v12 bitop3:0xde
	global_load_lds_dwordx4 v[0:1], off
	v_lshl_add_u64 v[0:1], v[8:9], 0, s[26:27]
	s_mov_b32 m0, s64
	s_add_i32 s14, s85, 0xa000
	global_load_lds_dwordx4 v[0:1], off
	v_lshl_add_u64 v[0:1], v[10:11], 0, s[26:27]
	s_mov_b32 m0, s14
	s_mov_b32 s81, s60
	global_load_lds_dwordx4 v[0:1], off
	s_add_i32 m0, s85, 0x1c000
	v_lshl_add_u64 v[0:1], v[4:5], 0, s[26:27]
	global_load_lds_dwordx4 v[0:1], off
	v_lshl_add_u64 v[0:1], v[6:7], 0, s[26:27]
	s_add_i32 m0, s85, 0x1e000
	s_cmp_gt_i32 s15, 63
	global_load_lds_dwordx4 v[0:1], off
	s_cselect_b64 s[88:89], -1, 0
	s_add_i32 s15, s13, -2
	s_cmpk_lt_u32 s16, 0x100
	s_cselect_b64 s[90:91], -1, 0
	s_and_b64 s[16:17], s[34:35], exec
	s_cselect_b32 s16, 4, 6
	s_lshl_b32 s17, s58, 3
	s_or_b32 s17, s17, 1
	s_waitcnt vmcnt(8)
	s_barrier
	s_waitcnt vmcnt(6)
	s_cmp_eq_u32 s46, 0
	s_cselect_b64 s[92:93], -1, 0
	s_cmp_lg_u32 s46, 0
	s_mov_b32 s33, 0
	s_cselect_b64 s[94:95], -1, 0
	s_add_i32 s78, s2, 0x10000
	v_lshl_add_u64 v[142:143], s[82:83], 0, v[136:137]
	v_lshl_add_u64 v[144:145], s[82:83], 0, v[138:139]
	v_add_u32_e32 v179, 0, v14
	s_barrier
	s_branch .LBB0_1210

; #define PG8_STAGE(bufoff, gbase, voff) do { _Pragma("unroll") for (int _i = 0; _i < 2; ++_i) \
;         __builtin_amdgcn_global_load_lds((const unsigned*)((const char*)(gbase) + (voff)[_i]), (PG8_LAS unsigned*)(lds + (bufoff) + ldsw + _i * 8192), 16, 0, 0); } while (0)
; #define PG8_WAIT_V(n) asm volatile("s_waitcnt vmcnt(" #n ")" ::: "memory")
; #define PG8_BAR __builtin_amdgcn_s_barrier()
; template <class Epi, class Sched, bool ALIGN_EPI = false, bool SP2 = false>
; __device__ __forceinline__ void gemm_phase(PG8_LAS unsigned char* lds, const Gemm g, const Sched& S, const Epi& E) {
;     ...
;         PG8_STAGE(PG8_SB(0, 0), cB, voffB); PG8_STAGE(PG8_SB(0, 1), cB + hstepB, voffB); PG8_STAGE(PG8_SA(0, 0), cA, voffA); PG8_STAGE(PG8_SA(0, 1), cA + hstepA, voffA);
;         if (wr == 1) PG8_BAR;
;         PG8_WAIT_V(2); PG8_BAR;
;         PG8_STAGE(PG8_SB(1, 0), cB + kstep, voffB); PG8_STAGE(PG8_SA(1, 0), cA + kstep, voffA); PG8_STAGE(PG8_SB(1, 1), cB + hstepB + kstep, voffB);
;         PG8_WAIT_V(6); PG8_BAR;
.LBB0_1448:
	v_readlane_b32 s4, v255, 18
	s_add_u32 s12, s4, 0x2000
	v_readlane_b32 s4, v255, 19
	v_bfe_u32 v165, v18, 4, 2
	s_addc_u32 s13, s4, 0
	v_and_b32_e32 v164, 15, v18
	v_lshlrev_b32_e32 v19, 4, v165
	v_lshlrev_b32_e32 v18, 2, v18
	s_lshl_b32 s16, s16, 5
	s_lshl_b32 s15, s17, 6
	v_lshl_or_b32 v19, v164, 6, v19
	s_lshl_b32 s17, s17, 13
	v_and_b32_e32 v18, 32, v18
	s_and_b32 s16, s16, 0x60
	v_bitop3_b32 v20, v19, s17, v18 bitop3:0xde
	s_lshl_b32 s17, s16, 7
	s_add_i32 m0, s8, 0x18000
	v_lshl_add_u64 v[0:1], v[0:1], 0, s[26:27]
	v_bitop3_b32 v166, v19, s17, v18 bitop3:0xde
	global_load_lds_dwordx4 v[0:1], off
	v_lshl_add_u64 v[0:1], v[2:3], 0, s[26:27]
	s_add_i32 m0, s8, 0x1a000
	s_add_i32 s17, s8, 0x8000
	global_load_lds_dwordx4 v[0:1], off
	v_lshl_add_u64 v[0:1], v[8:9], 0, s[26:27]
	s_mov_b32 m0, s17
	s_add_i32 s28, s8, 0xa000
	global_load_lds_dwordx4 v[0:1], off
	v_lshl_add_u64 v[0:1], v[10:11], 0, s[26:27]
	s_mov_b32 m0, s28
	s_ashr_i32 s14, s29, 31
	global_load_lds_dwordx4 v[0:1], off
	s_add_i32 m0, s8, 0x1c000
	v_lshl_add_u64 v[0:1], v[4:5], 0, s[26:27]
	global_load_lds_dwordx4 v[0:1], off
	v_lshl_add_u64 v[0:1], v[6:7], 0, s[26:27]
	s_add_i32 m0, s8, 0x1e000
	s_lshr_b32 s14, s14, 26
	global_load_lds_dwordx4 v[0:1], off
	s_add_i32 s14, s29, s14
	s_ashr_i32 s14, s14, 6
	s_cmp_gt_i32 s29, 63
	v_add_u32_e32 v0, v17, v15
	s_cselect_b64 s[46:47], -1, 0
	s_add_i32 s29, s14, -2
	v_add_lshl_u32 v0, v0, v16, 1
	v_mov_b32_e32 v1, v195
	s_waitcnt vmcnt(8)
	s_barrier
	s_waitcnt vmcnt(6)
	s_cmpk_lt_u32 s33, 0x100
	v_lshl_add_u64 v[152:153], s[80:81], 0, v[0:1]
	v_add_u32_e32 v0, v14, v12
	s_cselect_b64 s[52:53], -1, 0
	s_cmp_lg_u64 s[62:63], 0
	v_add_lshl_u32 v0, v0, v13, 1
	v_readlane_b32 s4, v254, 27
	s_cselect_b64 s[68:69], -1, 0
	v_lshl_add_u64 v[154:155], s[80:81], 0, v[0:1]
	s_mov_b32 s33, 0
	v_add_u32_e32 v167, 0, v20
	s_mov_b32 s59, s4
	v_readlane_b32 s64, v254, 22
	s_barrier
	v_readlane_b32 s5, v254, 28
	s_branch .LBB0_1451

; #define PG8_STAGE(bufoff, gbase, voff) do { _Pragma("unroll") for (int _i = 0; _i < 2; ++_i) \
;         __builtin_amdgcn_global_load_lds((const unsigned*)((const char*)(gbase) + (voff)[_i]), (PG8_LAS unsigned*)(lds + (bufoff) + ldsw + _i * 8192), 16, 0, 0); } while (0)
; #define PG8_WAIT_V(n) asm volatile("s_waitcnt vmcnt(" #n ")" ::: "memory")
; #define PG8_BAR __builtin_amdgcn_s_barrier()
; template <class Epi, class Sched, bool ALIGN_EPI = false, bool SP2 = false>
; __device__ __forceinline__ void gemm_phase(PG8_LAS unsigned char* lds, const Gemm g, const Sched& S, const Epi& E) {
;     ...
;         PG8_STAGE(PG8_SB(0, 0), cB, voffB); PG8_STAGE(PG8_SB(0, 1), cB + hstepB, voffB); PG8_STAGE(PG8_SA(0, 0), cA, voffA); PG8_STAGE(PG8_SA(0, 1), cA + hstepA, voffA);
;         if (wr == 1) PG8_BAR;
;         PG8_WAIT_V(2); PG8_BAR;
;         PG8_STAGE(PG8_SB(1, 0), cB + kstep, voffB); PG8_STAGE(PG8_SA(1, 0), cA + kstep, voffA); PG8_STAGE(PG8_SB(1, 1), cB + hstepB + kstep, voffB);
;         PG8_WAIT_V(6); PG8_BAR;
.LBB0_1478:
	v_bfe_u32 v163, v18, 4, 2
	v_and_b32_e32 v162, 15, v18
	v_lshlrev_b32_e32 v19, 4, v163
	v_lshlrev_b32_e32 v18, 2, v18
	s_lshl_b32 s15, s15, 5
	s_lshl_b32 s14, s16, 6
	v_lshl_or_b32 v19, v162, 6, v19
	s_lshl_b32 s16, s16, 13
	v_and_b32_e32 v18, 32, v18
	s_and_b32 s15, s15, 0x60
	v_bitop3_b32 v20, v19, s16, v18 bitop3:0xde
	s_lshl_b32 s16, s15, 7
	s_add_i32 m0, s2, 0x18000
	v_lshl_add_u64 v[0:1], v[0:1], 0, s[26:27]
	v_bitop3_b32 v164, v19, s16, v18 bitop3:0xde
	global_load_lds_dwordx4 v[0:1], off
	v_lshl_add_u64 v[0:1], v[2:3], 0, s[26:27]
	s_add_i32 m0, s2, 0x1a000
	s_add_i32 s16, s2, 0x8000
	global_load_lds_dwordx4 v[0:1], off
	v_lshl_add_u64 v[0:1], v[8:9], 0, s[26:27]
	s_mov_b32 m0, s16
	s_add_i32 s17, s2, 0xa000
	global_load_lds_dwordx4 v[0:1], off
	v_lshl_add_u64 v[0:1], v[10:11], 0, s[26:27]
	s_mov_b32 m0, s17
	s_lshr_b32 s13, s47, 26
	global_load_lds_dwordx4 v[0:1], off
	s_add_i32 m0, s2, 0x1c000
	v_lshl_add_u64 v[0:1], v[4:5], 0, s[26:27]
	global_load_lds_dwordx4 v[0:1], off
	v_lshl_add_u64 v[0:1], v[6:7], 0, s[26:27]
	s_add_i32 m0, s2, 0x1e000
	s_add_i32 s13, s46, s13
	global_load_lds_dwordx4 v[0:1], off
	s_ashr_i32 s13, s13, 6
	s_cmp_gt_i32 s46, 63
	v_add_u32_e32 v0, v17, v15
	s_cselect_b64 s[34:35], -1, 0
	s_lshl_b64 s[52:53], s[46:47], 1
	s_add_i32 s28, s13, -2
	v_add_lshl_u32 v0, v0, v16, 1
	v_mov_b32_e32 v1, v195
	s_waitcnt vmcnt(8)
	s_barrier
	s_waitcnt vmcnt(6)
	s_cmpk_lt_u32 s29, 0x100
	v_readlane_b32 s4, v255, 18
	v_lshl_add_u64 v[152:153], s[80:81], 0, v[0:1]
	v_add_u32_e32 v0, v14, v12
	s_cselect_b64 s[68:69], -1, 0
	s_add_u32 s76, s4, 0x62000
	v_readlane_b32 s4, v255, 19
	v_add_lshl_u32 v0, v0, v13, 1
	s_addc_u32 s77, s4, 0
	v_lshl_add_u64 v[154:155], s[80:81], 0, v[0:1]
	s_mov_b32 s29, 0
	v_add_u32_e32 v165, 0, v20
	v_readlane_b32 s58, v254, 37
	v_readlane_b32 s59, v254, 25
	s_barrier
	s_branch .LBB0_1481

; #define PG8_STAGE(bufoff, gbase, voff) do { _Pragma("unroll") for (int _i = 0; _i < 2; ++_i) \
;         __builtin_amdgcn_global_load_lds((const unsigned*)((const char*)(gbase) + (voff)[_i]), (PG8_LAS unsigned*)(lds + (bufoff) + ldsw + _i * 8192), 16, 0, 0); } while (0)
; #define PG8_WAIT_V(n) asm volatile("s_waitcnt vmcnt(" #n ")" ::: "memory")
; #define PG8_BAR __builtin_amdgcn_s_barrier()
; template <class Epi, class Sched, bool ALIGN_EPI = false, bool SP2 = false>
; __device__ __forceinline__ void gemm_phase(PG8_LAS unsigned char* lds, const Gemm g, const Sched& S, const Epi& E) {
;     ...
;         PG8_STAGE(PG8_SB(0, 0), cB, voffB); PG8_STAGE(PG8_SB(0, 1), cB + hstepB, voffB); PG8_STAGE(PG8_SA(0, 0), cA, voffA); PG8_STAGE(PG8_SA(0, 1), cA + hstepA, voffA);
;         if (wr == 1) PG8_BAR;
;         PG8_WAIT_V(2); PG8_BAR;
;         PG8_STAGE(PG8_SB(1, 0), cB + kstep, voffB); PG8_STAGE(PG8_SA(1, 0), cA + kstep, voffA); PG8_STAGE(PG8_SB(1, 1), cB + hstepB + kstep, voffB);
;         PG8_WAIT_V(6); PG8_BAR;
.LBB0_1619:
	v_bfe_u32 v141, v14, 4, 2
	s_ashr_i32 s16, s33, 31
	s_lshl_b32 s28, s28, 5
	v_and_b32_e32 v140, 15, v14
	s_lshr_b32 s16, s16, 26
	v_lshlrev_b32_e32 v15, 4, v141
	v_lshlrev_b32_e32 v14, 2, v14
	s_and_b32 s52, s28, 0x60
	s_add_i32 s16, s33, s16
	s_lshl_b32 s17, s29, 6
	v_lshl_or_b32 v15, v140, 6, v15
	s_lshl_b32 s29, s29, 13
	v_and_b32_e32 v14, 32, v14
	s_lshl_b32 s28, s52, 7
	s_add_i32 m0, s12, 0x18000
	v_lshl_add_u64 v[6:7], v[6:7], 0, s[26:27]
	s_ashr_i32 s16, s16, 6
	v_bitop3_b32 v16, v15, s29, v14 bitop3:0xde
	v_bitop3_b32 v142, v15, s28, v14 bitop3:0xde
	global_load_lds_dwordx4 v[6:7], off
	v_lshl_add_u64 v[4:5], v[4:5], 0, s[26:27]
	s_add_i32 m0, s12, 0x1a000
	s_add_i32 s28, s12, 0x8000
	s_add_i32 s29, s12, 0xa000
	global_load_lds_dwordx4 v[4:5], off
	v_lshl_add_u64 v[0:1], v[0:1], 0, s[26:27]
	s_mov_b32 m0, s28
	s_add_u32 s44, s88, 0x40080
	global_load_lds_dwordx4 v[0:1], off
	v_lshl_add_u64 v[0:1], v[2:3], 0, s[26:27]
	s_mov_b32 m0, s29
	s_addc_u32 s45, s89, 0
	global_load_lds_dwordx4 v[0:1], off
	s_add_i32 m0, s12, 0x1c000
	v_lshl_add_u64 v[0:1], s[44:45], 0, v[194:195]
	global_load_lds_dwordx4 v[0:1], off
	v_lshl_add_u64 v[0:1], s[44:45], 0, v[128:129]
	s_add_i32 m0, s12, 0x1e000
	s_cmp_gt_i32 s33, 63
	global_load_lds_dwordx4 v[0:1], off
	v_lshlrev_b32_e32 v0, 14, v12
	v_and_b32_e32 v0, 0xffff8000, v0
	v_lshl_add_u32 v0, v11, 11, v0
	v_and_b32_e32 v1, 1, v12
	v_lshl_or_b32 v0, v1, 6, v0
	v_lshl_add_u32 v134, v13, 1, v0
	v_lshlrev_b32_e32 v0, 14, v8
	v_and_b32_e32 v0, 0xffff8000, v0
	s_waitcnt vmcnt(8)
	s_barrier
	s_waitcnt vmcnt(6)
	s_cselect_b64 s[46:47], -1, 0
	s_add_i32 s33, s16, -2
	v_lshl_add_u32 v0, v9, 11, v0
	v_and_b32_e32 v1, 1, v8
	s_cmpk_lt_u32 s35, 0x100
	v_lshl_or_b32 v0, v1, 6, v0
	s_cselect_b64 s[48:49], -1, 0
	s_mov_b32 s35, s60
	v_mov_b32_e32 v135, v195
	v_lshl_add_u32 v136, v10, 1, v0
	v_mov_b32_e32 v137, v195
	s_mov_b32 s55, 0
	v_add_u32_e32 v143, 0, v16
	s_lshl_b32 s52, s52, 1
	s_barrier
	s_branch .LBB0_1622

; #define PG8_STAGE(bufoff, gbase, voff) do { _Pragma("unroll") for (int _i = 0; _i < 2; ++_i) \
;         __builtin_amdgcn_global_load_lds((const unsigned*)((const char*)(gbase) + (voff)[_i]), (PG8_LAS unsigned*)(lds + (bufoff) + ldsw + _i * 8192), 16, 0, 0); } while (0)
; #define PG8_WAIT_V(n) asm volatile("s_waitcnt vmcnt(" #n ")" ::: "memory")
; #define PG8_BAR __builtin_amdgcn_s_barrier()
; template <class Epi, class Sched, bool ALIGN_EPI = false, bool SP2 = false>
; __device__ __forceinline__ void gemm_phase(PG8_LAS unsigned char* lds, const Gemm g, const Sched& S, const Epi& E) {
;     ...
;         PG8_STAGE(PG8_SB(0, 0), cB, voffB); PG8_STAGE(PG8_SB(0, 1), cB + hstepB, voffB); PG8_STAGE(PG8_SA(0, 0), cA, voffA); PG8_STAGE(PG8_SA(0, 1), cA + hstepA, voffA);
;         if (wr == 1) PG8_BAR;
;         PG8_WAIT_V(2); PG8_BAR;
;         PG8_STAGE(PG8_SB(1, 0), cB + kstep, voffB); PG8_STAGE(PG8_SA(1, 0), cA + kstep, voffA); PG8_STAGE(PG8_SB(1, 1), cB + hstepB + kstep, voffB);
;         PG8_WAIT_V(6); PG8_BAR;
.LBB0_1688:
	v_readlane_b32 s4, v255, 18
	s_add_u32 s11, s4, 0x5000
	v_readlane_b32 s4, v255, 19
	v_bfe_u32 v167, v10, 4, 2
	s_addc_u32 s12, s4, 0
	v_and_b32_e32 v166, 15, v10
	s_ashr_i32 s13, s28, 31
	v_lshlrev_b32_e32 v11, 4, v167
	v_lshlrev_b32_e32 v10, 2, v10
	s_lshl_b32 s15, s15, 5
	v_readlane_b32 s62, v254, 33
	s_lshr_b32 s13, s13, 26
	s_lshl_b32 s14, s16, 6
	v_lshl_or_b32 v11, v166, 6, v11
	s_lshl_b32 s16, s16, 13
	v_and_b32_e32 v10, 32, v10
	s_and_b32 s15, s15, 0x60
	v_mov_b32_e32 v133, v195
	v_readlane_b32 s63, v254, 34
	s_add_i32 s13, s28, s13
	v_bitop3_b32 v16, v11, s16, v10 bitop3:0xde
	s_lshl_b32 s16, s15, 7
	s_add_i32 m0, s3, 0x18000
	v_lshl_add_u64 v[0:1], v[0:1], 0, s[26:27]
	v_lshl_add_u64 v[12:13], s[62:63], 0, v[132:133]
	v_mov_b32_e32 v131, v195
	s_ashr_i32 s13, s13, 6
	v_bitop3_b32 v168, v11, s16, v10 bitop3:0xde
	global_load_lds_dwordx4 v[0:1], off
	v_lshl_add_u64 v[0:1], v[2:3], 0, s[26:27]
	s_add_i32 m0, s3, 0x1a000
	s_add_i32 s16, s3, 0x8000
	s_add_i32 s17, s3, 0xa000
	v_lshl_add_u64 v[14:15], s[62:63], 0, v[130:131]
	global_load_lds_dwordx4 v[0:1], off
	v_lshl_add_u64 v[0:1], v[12:13], 0, s[26:27]
	s_mov_b32 m0, s16
	s_add_u32 s34, s68, 0x100080
	global_load_lds_dwordx4 v[0:1], off
	v_lshl_add_u64 v[0:1], v[14:15], 0, s[26:27]
	s_mov_b32 m0, s17
	s_addc_u32 s35, s69, 0
	global_load_lds_dwordx4 v[0:1], off
	s_add_i32 m0, s3, 0x1c000
	v_lshl_add_u64 v[0:1], s[34:35], 0, v[194:195]
	global_load_lds_dwordx4 v[0:1], off
	v_lshl_add_u64 v[0:1], s[34:35], 0, v[128:129]
	s_add_i32 m0, s3, 0x1e000
	s_cmp_gt_i32 s28, 63
	global_load_lds_dwordx4 v[0:1], off
	v_lshlrev_b32_e32 v0, 16, v8
	v_and_b32_e32 v0, 0xfffe0000, v0
	v_lshl_add_u32 v0, v7, 13, v0
	v_and_b32_e32 v1, 1, v8
	v_lshl_or_b32 v0, v1, 6, v0
	v_lshl_add_u32 v134, v9, 1, v0
	v_lshlrev_b32_e32 v0, 16, v4
	v_and_b32_e32 v0, 0xfffe0000, v0
	s_waitcnt vmcnt(8)
	s_barrier
	s_waitcnt vmcnt(6)
	s_cselect_b64 s[34:35], -1, 0
	s_add_i32 s28, s13, -2
	v_lshl_add_u32 v0, v5, 13, v0
	v_and_b32_e32 v1, 1, v4
	s_cmpk_lt_u32 s29, 0x100
	v_lshl_or_b32 v0, v1, 6, v0
	v_readlane_b32 s4, v254, 27
	s_cselect_b64 s[36:37], -1, 0
	v_mov_b32_e32 v135, v195
	v_lshl_add_u32 v136, v6, 1, v0
	v_mov_b32_e32 v137, v195
	s_mov_b32 s29, 0
	v_add_u32_e32 v169, 0, v16
	s_mov_b32 s58, s4
	v_readlane_b32 s33, v254, 22
	s_barrier
	v_readlane_b32 s5, v254, 28
	s_branch .LBB0_1691

; #define PG8_STAGE(bufoff, gbase, voff) do { _Pragma("unroll") for (int _i = 0; _i < 2; ++_i) \
;         __builtin_amdgcn_global_load_lds((const unsigned*)((const char*)(gbase) + (voff)[_i]), (PG8_LAS unsigned*)(lds + (bufoff) + ldsw + _i * 8192), 16, 0, 0); } while (0)
; #define PG8_WAIT_V(n) asm volatile("s_waitcnt vmcnt(" #n ")" ::: "memory")
; #define PG8_BAR __builtin_amdgcn_s_barrier()
; template <class Epi, class Sched, bool ALIGN_EPI = false, bool SP2 = false>
; __device__ __forceinline__ void gemm_phase(PG8_LAS unsigned char* lds, const Gemm g, const Sched& S, const Epi& E) {
;     ...
;         PG8_STAGE(PG8_SB(0, 0), cB, voffB); PG8_STAGE(PG8_SB(0, 1), cB + hstepB, voffB); PG8_STAGE(PG8_SA(0, 0), cA, voffA); PG8_STAGE(PG8_SA(0, 1), cA + hstepA, voffA);
;         if (wr == 1) PG8_BAR;
;         PG8_WAIT_V(2); PG8_BAR;
;         PG8_STAGE(PG8_SB(1, 0), cB + kstep, voffB); PG8_STAGE(PG8_SA(1, 0), cA + kstep, voffA); PG8_STAGE(PG8_SB(1, 1), cB + hstepB + kstep, voffB);
;         PG8_WAIT_V(6); PG8_BAR;
.LBB0_1711:
	v_bfe_u32 v171, v14, 4, 2
	v_and_b32_e32 v170, 15, v14
	v_lshlrev_b32_e32 v15, 4, v171
	v_lshlrev_b32_e32 v14, 2, v14
	s_lshl_b32 s13, s13, 5
	s_lshr_b32 s11, s37, 26
	s_lshl_b32 s12, s14, 6
	v_lshl_or_b32 v15, v170, 6, v15
	s_lshl_b32 s14, s14, 13
	v_and_b32_e32 v14, 32, v14
	s_and_b32 s13, s13, 0x60
	s_add_i32 s11, s36, s11
	v_bitop3_b32 v16, v15, s14, v14 bitop3:0xde
	s_lshl_b32 s14, s13, 7
	s_add_i32 m0, s3, 0x18000
	v_lshl_add_u64 v[6:7], v[6:7], 0, s[26:27]
	s_ashr_i32 s11, s11, 6
	v_bitop3_b32 v172, v15, s14, v14 bitop3:0xde
	global_load_lds_dwordx4 v[6:7], off
	v_lshl_add_u64 v[4:5], v[4:5], 0, s[26:27]
	s_add_i32 m0, s3, 0x1a000
	s_add_i32 s14, s3, 0x8000
	s_add_i32 s15, s3, 0xa000
	global_load_lds_dwordx4 v[4:5], off
	v_lshl_add_u64 v[0:1], v[0:1], 0, s[26:27]
	s_mov_b32 m0, s14
	s_add_u32 s28, s62, 0x100080
	global_load_lds_dwordx4 v[0:1], off
	v_lshl_add_u64 v[0:1], v[2:3], 0, s[26:27]
	s_mov_b32 m0, s15
	s_addc_u32 s29, s63, 0
	global_load_lds_dwordx4 v[0:1], off
	s_add_i32 m0, s3, 0x1c000
	v_lshl_add_u64 v[0:1], s[28:29], 0, v[194:195]
	global_load_lds_dwordx4 v[0:1], off
	v_lshl_add_u64 v[0:1], s[28:29], 0, v[128:129]
	s_add_i32 m0, s3, 0x1e000
	s_cmp_gt_i32 s36, 63
	global_load_lds_dwordx4 v[0:1], off
	v_lshlrev_b32_e32 v0, 16, v12
	v_and_b32_e32 v0, 0xfffe0000, v0
	v_lshl_add_u32 v0, v11, 13, v0
	v_and_b32_e32 v1, 1, v12
	v_lshl_or_b32 v0, v1, 6, v0
	v_lshl_add_u32 v134, v13, 1, v0
	v_lshlrev_b32_e32 v0, 16, v8
	s_cselect_b64 s[34:35], -1, 0
	s_lshl_b64 s[36:37], s[36:37], 1
	s_add_i32 s16, s11, -2
	v_and_b32_e32 v0, 0xfffe0000, v0
	s_waitcnt vmcnt(8)
	s_barrier
	s_waitcnt vmcnt(6)
	s_cmpk_lt_u32 s17, 0x100
	v_readlane_b32 s4, v255, 18
	v_lshl_add_u32 v0, v9, 13, v0
	v_and_b32_e32 v1, 1, v8
	s_cselect_b64 s[42:43], -1, 0
	s_add_u32 s44, s4, 0x65000
	v_readlane_b32 s4, v255, 19
	v_lshl_or_b32 v0, v1, 6, v0
	s_addc_u32 s45, s4, 0
	v_mov_b32_e32 v135, v195
	v_lshl_add_u32 v136, v10, 1, v0
	v_mov_b32_e32 v137, v195
	s_mov_b32 s17, 0
	v_add_u32_e32 v173, 0, v16
	v_readlane_b32 s33, v254, 37
	v_readlane_b32 s29, v254, 25
	s_barrier
	s_branch .LBB0_1714
